# v12 + the 16th UP H store of each tile also write-through non-temporal (sc1 nt)
# speedup vs baseline: 1.0165x; 1.0165x over previous
; #define PG8_LAS __attribute__((address_space(3)))
; __device__ __forceinline__ unsigned cvtpk(float lo, float hi) { f32x2_t v = {lo, hi}; f16x2_t b = __builtin_convertvector(v, f16x2_t); return __builtin_bit_cast(unsigned, b); }
;     __device__ __forceinline__ void operator()(const f32x4 (&acc)[2][2][4][2], const Unit& u, int wr, int wc, int fr, int fq) const {
;         const int row0 = u.pm * BM + wr * 64 + fr, col0 = u.pn * BM + wc * 32 + 8 * fq;
;         float rs[2][4]; const PG8_LAS float* tb = rsl + (u.pm == pmA ? 0 : 256);
; #pragma unroll
;         for (int ai = 0; ai < 2; ++ai)
; #pragma unroll
;             for (int m = 0; m < 4; ++m) rs[ai][m] = tb[ai * HALF + wr * 64 + m * 16 + fr];
; #pragma unroll
;         for (int ai = 0; ai < 2; ++ai)
; #pragma unroll
;             for (int m = 0; m < 4; ++m) { const int row = row0 + ai * HALF + m * 16; bf16_t* rowp = H + (size_t)row * 4096 + col0;
; #pragma unroll
;                 for (int bj = 0; bj < 2; ++bj) { f32x4 v0 = acc[ai][bj][m][0] * rs[ai][m], v1 = acc[ai][bj][m][1] * rs[ai][m];
; #pragma unroll
;                     for (int e = 0; e < 4; ++e) { const float a = fmaxf(v0[e], 0.f), b = fmaxf(v1[e], 0.f); v0[e] = a * a; v1[e] = b * b; }
;                     u32x4 w; w.x = cvtpk(v0[0], v0[1]); w.y = cvtpk(v0[2], v0[3]); w.z = cvtpk(v1[0], v1[1]); w.w = cvtpk(v1[2], v1[3]);
;                     *(u32x4*)(rowp + bj * HALF) = w; } }
.LBB0_970:
	v_readlane_b32 s21, v255, 57
	s_cmp_eq_u32 s42, s21
	s_cselect_b32 s21, 0, 0x400
	v_add_u32_e32 v140, s21, v153
	v_lshl_add_u32 v148, s42, 8, v151
	ds_read2_b32 v[156:157], v140 offset1:16
	ds_read2_b32 v[146:147], v140 offset0:32 offset1:48
	ds_read2_b32 v[144:145], v140 offset0:128 offset1:144
	ds_read2_b32 v[142:143], v140 offset0:160 offset1:176
	v_lshl_or_b32 v140, s53, 8, v154
	v_ashrrev_i32_e32 v149, 31, v148
	v_ashrrev_i32_e32 v141, 31, v140
	v_lshlrev_b64 v[158:159], 13, v[148:149]
	s_waitcnt lgkmcnt(0)
	v_pk_mul_f32 v[122:123], v[122:123], v[156:157] op_sel_hi:[1,0]
	v_lshl_add_u64 v[158:159], s[74:75], 0, v[158:159]
	v_lshlrev_b64 v[160:161], 1, v[140:141]
	v_pk_mul_f32 v[128:129], v[128:129], v[156:157] op_sel_hi:[1,0]
	v_pk_mul_f32 v[126:127], v[126:127], v[156:157] op_sel_hi:[1,0]
	v_pk_mul_f32 v[124:125], v[124:125], v[156:157] op_sel_hi:[1,0]
	v_max_f32_e32 v122, 0, v122
	v_max_f32_e32 v123, 0, v123
	v_lshl_add_u64 v[140:141], v[158:159], 0, v[160:161]
	v_max_f32_e32 v126, 0, v126
	v_max_f32_e32 v127, 0, v127
	v_pk_mul_f32 v[158:159], v[122:123], v[122:123]
	v_max_f32_e32 v122, 0, v128
	v_max_f32_e32 v124, 0, v124
	v_max_f32_e32 v123, 0, v129
	v_max_f32_e32 v125, 0, v125
	v_pk_mul_f32 v[126:127], v[126:127], v[126:127]
	v_pk_mul_f32 v[128:129], v[122:123], v[122:123]
	v_pk_mul_f32 v[172:173], v[124:125], v[124:125]
	v_pk_mul_f32 v[114:115], v[114:115], v[156:157] op_sel_hi:[1,0]
	v_cvt_pk_f16_f32 v122, v126, v127
	v_cvt_pk_f16_f32 v123, v128, v129
	v_cvt_pk_f16_f32 v124, v158, v159
	v_cvt_pk_f16_f32 v125, v172, v173
	v_pk_mul_f32 v[120:121], v[120:121], v[156:157] op_sel_hi:[1,0]
	v_pk_mul_f32 v[118:119], v[118:119], v[156:157] op_sel_hi:[1,0]
	v_pk_mul_f32 v[116:117], v[116:117], v[156:157] op_sel_hi:[1,0]
	v_max_f32_e32 v114, 0, v114
	v_max_f32_e32 v115, 0, v115
	global_store_dwordx4 v[140:141], v[122:125], off sc1 nt
	v_max_f32_e32 v118, 0, v118
	v_max_f32_e32 v119, 0, v119
	v_pk_mul_f32 v[122:123], v[114:115], v[114:115]
	v_max_f32_e32 v114, 0, v120
	v_max_f32_e32 v116, 0, v116
	v_max_f32_e32 v115, 0, v121
	v_max_f32_e32 v117, 0, v117
	v_pk_mul_f32 v[118:119], v[118:119], v[118:119]
	v_pk_mul_f32 v[120:121], v[114:115], v[114:115]
	v_pk_mul_f32 v[124:125], v[116:117], v[116:117]
	v_cvt_pk_f16_f32 v114, v118, v119
	v_cvt_pk_f16_f32 v115, v120, v121
	v_cvt_pk_f16_f32 v116, v122, v123
	v_cvt_pk_f16_f32 v117, v124, v125
	global_store_dwordx4 v[140:141], v[114:117], off offset:256 sc1 nt
	v_pk_mul_f32 v[90:91], v[90:91], v[146:147] op_sel_hi:[1,0]
	v_pk_mul_f32 v[96:97], v[96:97], v[146:147] op_sel_hi:[1,0]
	v_mov_b32_e32 v116, v157
	v_or_b32_e32 v114, 16, v148
	v_pk_mul_f32 v[106:107], v[106:107], v[116:117] op_sel_hi:[1,0]
	v_ashrrev_i32_e32 v115, 31, v114
	v_pk_mul_f32 v[112:113], v[112:113], v[116:117] op_sel_hi:[1,0]
	v_pk_mul_f32 v[110:111], v[110:111], v[116:117] op_sel_hi:[1,0]
	v_pk_mul_f32 v[108:109], v[108:109], v[116:117] op_sel_hi:[1,0]
	v_max_f32_e32 v106, 0, v106
	v_max_f32_e32 v107, 0, v107
	v_lshlrev_b64 v[114:115], 13, v[114:115]
	v_max_f32_e32 v110, 0, v110
	v_max_f32_e32 v111, 0, v111
	v_pk_mul_f32 v[118:119], v[106:107], v[106:107]
	v_max_f32_e32 v106, 0, v112
	v_max_f32_e32 v108, 0, v108
	v_max_f32_e32 v107, 0, v113
	v_max_f32_e32 v109, 0, v109
	v_lshl_add_u64 v[114:115], s[74:75], 0, v[114:115]
	v_pk_mul_f32 v[110:111], v[110:111], v[110:111]
	v_pk_mul_f32 v[112:113], v[106:107], v[106:107]
	v_pk_mul_f32 v[120:121], v[108:109], v[108:109]
	v_pk_mul_f32 v[98:99], v[98:99], v[116:117] op_sel_hi:[1,0]
	v_lshl_add_u64 v[114:115], v[114:115], 0, v[160:161]
	v_cvt_pk_f16_f32 v106, v110, v111
	v_cvt_pk_f16_f32 v107, v112, v113
	v_cvt_pk_f16_f32 v108, v118, v119
	v_cvt_pk_f16_f32 v109, v120, v121
	v_pk_mul_f32 v[104:105], v[104:105], v[116:117] op_sel_hi:[1,0]
	v_pk_mul_f32 v[102:103], v[102:103], v[116:117] op_sel_hi:[1,0]
	v_pk_mul_f32 v[100:101], v[100:101], v[116:117] op_sel_hi:[1,0]
	v_max_f32_e32 v98, 0, v98
	v_max_f32_e32 v99, 0, v99
	global_store_dwordx4 v[114:115], v[106:109], off sc1 nt
	v_max_f32_e32 v102, 0, v102
	v_max_f32_e32 v103, 0, v103
	v_pk_mul_f32 v[106:107], v[98:99], v[98:99]
	v_max_f32_e32 v98, 0, v104
	v_max_f32_e32 v100, 0, v100
	v_max_f32_e32 v99, 0, v105
	v_max_f32_e32 v101, 0, v101
	v_pk_mul_f32 v[102:103], v[102:103], v[102:103]
	v_pk_mul_f32 v[104:105], v[98:99], v[98:99]
	v_pk_mul_f32 v[108:109], v[100:101], v[100:101]
	v_cvt_pk_f16_f32 v98, v102, v103
	v_cvt_pk_f16_f32 v99, v104, v105
	v_cvt_pk_f16_f32 v100, v106, v107
	v_cvt_pk_f16_f32 v101, v108, v109
	global_store_dwordx4 v[114:115], v[98:101], off offset:256 sc1 nt
	v_pk_mul_f32 v[94:95], v[94:95], v[146:147] op_sel_hi:[1,0]
	v_pk_mul_f32 v[92:93], v[92:93], v[146:147] op_sel_hi:[1,0]
	v_or_b32_e32 v98, 32, v148
	v_ashrrev_i32_e32 v99, 31, v98
	v_max_f32_e32 v90, 0, v90
	v_max_f32_e32 v91, 0, v91
	v_lshlrev_b64 v[98:99], 13, v[98:99]
	v_max_f32_e32 v94, 0, v94
	v_max_f32_e32 v95, 0, v95
	v_pk_mul_f32 v[100:101], v[90:91], v[90:91]
	v_max_f32_e32 v90, 0, v96
	v_max_f32_e32 v92, 0, v92
	v_max_f32_e32 v91, 0, v97
	v_max_f32_e32 v93, 0, v93
	v_lshl_add_u64 v[98:99], s[74:75], 0, v[98:99]
	v_pk_mul_f32 v[94:95], v[94:95], v[94:95]
	v_pk_mul_f32 v[96:97], v[90:91], v[90:91]
	v_pk_mul_f32 v[102:103], v[92:93], v[92:93]
	v_pk_mul_f32 v[82:83], v[82:83], v[146:147] op_sel_hi:[1,0]
	v_lshl_add_u64 v[98:99], v[98:99], 0, v[160:161]
	v_cvt_pk_f16_f32 v90, v94, v95
	v_cvt_pk_f16_f32 v91, v96, v97
	v_cvt_pk_f16_f32 v92, v100, v101
	v_cvt_pk_f16_f32 v93, v102, v103
	v_pk_mul_f32 v[88:89], v[88:89], v[146:147] op_sel_hi:[1,0]
	v_pk_mul_f32 v[86:87], v[86:87], v[146:147] op_sel_hi:[1,0]
	v_pk_mul_f32 v[84:85], v[84:85], v[146:147] op_sel_hi:[1,0]
; __device__ __forceinline__ unsigned cvtpk(float lo, float hi) { f32x2_t v = {lo, hi}; f16x2_t b = __builtin_convertvector(v, f16x2_t); return __builtin_bit_cast(unsigned, b); }
;     __device__ __forceinline__ void operator()(const f32x4 (&acc)[2][2][4][2], const Unit& u, int wr, int wc, int fr, int fq) const {
;     ...
; #pragma unroll
;         for (int ai = 0; ai < 2; ++ai)
; #pragma unroll
;             for (int m = 0; m < 4; ++m) { const int row = row0 + ai * HALF + m * 16; bf16_t* rowp = H + (size_t)row * 4096 + col0;
; #pragma unroll
;                 for (int bj = 0; bj < 2; ++bj) { f32x4 v0 = acc[ai][bj][m][0] * rs[ai][m], v1 = acc[ai][bj][m][1] * rs[ai][m];
; #pragma unroll
;                     for (int e = 0; e < 4; ++e) { const float a = fmaxf(v0[e], 0.f), b = fmaxf(v1[e], 0.f); v0[e] = a * a; v1[e] = b * b; }
;                     u32x4 w; w.x = cvtpk(v0[0], v0[1]); w.y = cvtpk(v0[2], v0[3]); w.z = cvtpk(v1[0], v1[1]); w.w = cvtpk(v1[2], v1[3]);
;                     *(u32x4*)(rowp + bj * HALF) = w; } }
	v_max_f32_e32 v82, 0, v82
	v_max_f32_e32 v83, 0, v83
	global_store_dwordx4 v[98:99], v[90:93], off sc1 nt
	v_max_f32_e32 v86, 0, v86
	v_max_f32_e32 v87, 0, v87
	v_pk_mul_f32 v[90:91], v[82:83], v[82:83]
	v_max_f32_e32 v82, 0, v88
	v_max_f32_e32 v84, 0, v84
	v_max_f32_e32 v83, 0, v89
	v_max_f32_e32 v85, 0, v85
	v_pk_mul_f32 v[86:87], v[86:87], v[86:87]
	v_pk_mul_f32 v[88:89], v[82:83], v[82:83]
	v_pk_mul_f32 v[92:93], v[84:85], v[84:85]
	v_cvt_pk_f16_f32 v82, v86, v87
	v_cvt_pk_f16_f32 v83, v88, v89
	v_cvt_pk_f16_f32 v84, v90, v91
	v_cvt_pk_f16_f32 v85, v92, v93
	global_store_dwordx4 v[98:99], v[82:85], off offset:256 sc1 nt
	v_pk_mul_f32 v[62:63], v[62:63], v[144:145] op_sel_hi:[1,0]
	v_pk_mul_f32 v[58:59], v[58:59], v[144:145] op_sel_hi:[1,0]
	v_mov_b32_e32 v84, v147
	v_or_b32_e32 v82, 48, v148
	v_pk_mul_f32 v[74:75], v[74:75], v[84:85] op_sel_hi:[1,0]
	v_ashrrev_i32_e32 v83, 31, v82
	v_pk_mul_f32 v[80:81], v[80:81], v[84:85] op_sel_hi:[1,0]
	v_pk_mul_f32 v[78:79], v[78:79], v[84:85] op_sel_hi:[1,0]
	v_pk_mul_f32 v[76:77], v[76:77], v[84:85] op_sel_hi:[1,0]
	v_max_f32_e32 v74, 0, v74
	v_max_f32_e32 v75, 0, v75
	v_lshlrev_b64 v[82:83], 13, v[82:83]
	v_max_f32_e32 v78, 0, v78
	v_max_f32_e32 v79, 0, v79
	v_pk_mul_f32 v[86:87], v[74:75], v[74:75]
	v_max_f32_e32 v74, 0, v80
	v_max_f32_e32 v76, 0, v76
	v_max_f32_e32 v75, 0, v81
	v_max_f32_e32 v77, 0, v77
	v_lshl_add_u64 v[82:83], s[74:75], 0, v[82:83]
	v_pk_mul_f32 v[78:79], v[78:79], v[78:79]
	v_pk_mul_f32 v[80:81], v[74:75], v[74:75]
	v_pk_mul_f32 v[88:89], v[76:77], v[76:77]
	v_pk_mul_f32 v[66:67], v[66:67], v[84:85] op_sel_hi:[1,0]
	v_lshl_add_u64 v[82:83], v[82:83], 0, v[160:161]
	v_cvt_pk_f16_f32 v74, v78, v79
	v_cvt_pk_f16_f32 v75, v80, v81
	v_cvt_pk_f16_f32 v76, v86, v87
	v_cvt_pk_f16_f32 v77, v88, v89
	v_pk_mul_f32 v[72:73], v[72:73], v[84:85] op_sel_hi:[1,0]
	v_pk_mul_f32 v[70:71], v[70:71], v[84:85] op_sel_hi:[1,0]
	v_pk_mul_f32 v[68:69], v[68:69], v[84:85] op_sel_hi:[1,0]
	v_max_f32_e32 v66, 0, v66
	v_max_f32_e32 v67, 0, v67
	global_store_dwordx4 v[82:83], v[74:77], off sc1 nt
	v_max_f32_e32 v70, 0, v70
	v_max_f32_e32 v71, 0, v71
	v_pk_mul_f32 v[74:75], v[66:67], v[66:67]
	v_max_f32_e32 v66, 0, v72
	v_max_f32_e32 v68, 0, v68
	v_max_f32_e32 v67, 0, v73
	v_max_f32_e32 v69, 0, v69
	v_pk_mul_f32 v[70:71], v[70:71], v[70:71]
	v_pk_mul_f32 v[72:73], v[66:67], v[66:67]
	v_pk_mul_f32 v[76:77], v[68:69], v[68:69]
	v_cvt_pk_f16_f32 v66, v70, v71
	v_cvt_pk_f16_f32 v67, v72, v73
	v_cvt_pk_f16_f32 v68, v74, v75
	v_cvt_pk_f16_f32 v69, v76, v77
	v_pk_mul_f32 v[64:65], v[64:65], v[144:145] op_sel_hi:[1,0]
	v_pk_mul_f32 v[60:61], v[60:61], v[144:145] op_sel_hi:[1,0]
	v_max_f32_e32 v62, 0, v62
	v_max_f32_e32 v58, 0, v58
	v_max_f32_e32 v63, 0, v63
	v_max_f32_e32 v59, 0, v59
	global_store_dwordx4 v[82:83], v[66:69], off offset:256 sc1 nt
	v_pk_mul_f32 v[62:63], v[62:63], v[62:63]
	v_max_f32_e32 v60, 0, v60
	v_pk_mul_f32 v[68:69], v[58:59], v[58:59]
	v_max_f32_e32 v58, 0, v64
	v_max_f32_e32 v59, 0, v65
	v_max_f32_e32 v61, 0, v61
	s_mov_b32 s21, 0x100000
	v_pk_mul_f32 v[64:65], v[58:59], v[58:59]
	v_pk_mul_f32 v[70:71], v[60:61], v[60:61]
	v_cvt_pk_f16_f32 v58, v62, v63
	v_add_co_u32_e32 v62, vcc, s21, v140
	v_pk_mul_f32 v[50:51], v[50:51], v[144:145] op_sel_hi:[1,0]
	v_cvt_pk_f16_f32 v59, v64, v65
	v_cvt_pk_f16_f32 v60, v68, v69
	v_cvt_pk_f16_f32 v61, v70, v71
	v_addc_co_u32_e32 v63, vcc, 0, v141, vcc
	v_pk_mul_f32 v[56:57], v[56:57], v[144:145] op_sel_hi:[1,0]
	v_pk_mul_f32 v[54:55], v[54:55], v[144:145] op_sel_hi:[1,0]
	v_pk_mul_f32 v[52:53], v[52:53], v[144:145] op_sel_hi:[1,0]
	v_max_f32_e32 v50, 0, v50
	v_max_f32_e32 v51, 0, v51
	global_store_dwordx4 v[62:63], v[58:61], off sc1 nt
	v_max_f32_e32 v54, 0, v54
	v_max_f32_e32 v55, 0, v55
	v_pk_mul_f32 v[58:59], v[50:51], v[50:51]
	v_max_f32_e32 v50, 0, v56
	v_max_f32_e32 v52, 0, v52
	v_max_f32_e32 v51, 0, v57
	v_max_f32_e32 v53, 0, v53
	s_mov_b64 s[26:27], 0x100000
	v_pk_mul_f32 v[54:55], v[54:55], v[54:55]
	v_pk_mul_f32 v[56:57], v[50:51], v[50:51]
	v_pk_mul_f32 v[60:61], v[52:53], v[52:53]
	v_lshl_add_u64 v[66:67], v[140:141], 0, s[26:27]
	v_cvt_pk_f16_f32 v50, v54, v55
	v_cvt_pk_f16_f32 v51, v56, v57
	v_cvt_pk_f16_f32 v52, v58, v59
	v_cvt_pk_f16_f32 v53, v60, v61
	global_store_dwordx4 v[66:67], v[50:53], off offset:256 sc1 nt
	s_mov_b32 s21, 0x120000
	s_mov_b64 s[26:27], 0x120000
	v_mov_b32_e32 v52, v145
	v_pk_mul_f32 v[46:47], v[46:47], v[52:53] op_sel_hi:[1,0]
	v_pk_mul_f32 v[42:43], v[42:43], v[52:53] op_sel_hi:[1,0]
	v_pk_mul_f32 v[48:49], v[48:49], v[52:53] op_sel_hi:[1,0]
	v_pk_mul_f32 v[44:45], v[44:45], v[52:53] op_sel_hi:[1,0]
	v_max_f32_e32 v46, 0, v46
	v_max_f32_e32 v42, 0, v42
	v_max_f32_e32 v47, 0, v47
	v_max_f32_e32 v43, 0, v43
	v_pk_mul_f32 v[46:47], v[46:47], v[46:47]
	v_pk_mul_f32 v[54:55], v[42:43], v[42:43]
	v_max_f32_e32 v42, 0, v48
	v_max_f32_e32 v44, 0, v44
	v_max_f32_e32 v43, 0, v49
	v_max_f32_e32 v45, 0, v45
	v_pk_mul_f32 v[48:49], v[42:43], v[42:43]
	v_pk_mul_f32 v[56:57], v[44:45], v[44:45]
	v_cvt_pk_f16_f32 v42, v46, v47
; __device__ __forceinline__ unsigned cvtpk(float lo, float hi) { f32x2_t v = {lo, hi}; f16x2_t b = __builtin_convertvector(v, f16x2_t); return __builtin_bit_cast(unsigned, b); }
;     __device__ __forceinline__ void operator()(const f32x4 (&acc)[2][2][4][2], const Unit& u, int wr, int wc, int fr, int fq) const {
;     ...
; #pragma unroll
;         for (int ai = 0; ai < 2; ++ai)
; #pragma unroll
;             for (int m = 0; m < 4; ++m) { const int row = row0 + ai * HALF + m * 16; bf16_t* rowp = H + (size_t)row * 4096 + col0;
; #pragma unroll
;                 for (int bj = 0; bj < 2; ++bj) { f32x4 v0 = acc[ai][bj][m][0] * rs[ai][m], v1 = acc[ai][bj][m][1] * rs[ai][m];
; #pragma unroll
;                     for (int e = 0; e < 4; ++e) { const float a = fmaxf(v0[e], 0.f), b = fmaxf(v1[e], 0.f); v0[e] = a * a; v1[e] = b * b; }
;                     u32x4 w; w.x = cvtpk(v0[0], v0[1]); w.y = cvtpk(v0[2], v0[3]); w.z = cvtpk(v1[0], v1[1]); w.w = cvtpk(v1[2], v1[3]);
;                     *(u32x4*)(rowp + bj * HALF) = w; } }
	v_add_co_u32_e32 v46, vcc, s21, v140
	v_pk_mul_f32 v[34:35], v[34:35], v[52:53] op_sel_hi:[1,0]
	v_cvt_pk_f16_f32 v43, v48, v49
	v_cvt_pk_f16_f32 v44, v54, v55
	v_cvt_pk_f16_f32 v45, v56, v57
	v_addc_co_u32_e32 v47, vcc, 0, v141, vcc
	v_pk_mul_f32 v[40:41], v[40:41], v[52:53] op_sel_hi:[1,0]
	v_pk_mul_f32 v[38:39], v[38:39], v[52:53] op_sel_hi:[1,0]
	v_pk_mul_f32 v[36:37], v[36:37], v[52:53] op_sel_hi:[1,0]
	v_max_f32_e32 v34, 0, v34
	v_max_f32_e32 v35, 0, v35
	global_store_dwordx4 v[46:47], v[42:45], off sc1 nt
	v_max_f32_e32 v38, 0, v38
	v_max_f32_e32 v39, 0, v39
	v_pk_mul_f32 v[42:43], v[34:35], v[34:35]
	v_max_f32_e32 v34, 0, v40
	v_max_f32_e32 v36, 0, v36
	v_max_f32_e32 v35, 0, v41
	v_max_f32_e32 v37, 0, v37
	v_pk_mul_f32 v[38:39], v[38:39], v[38:39]
	v_pk_mul_f32 v[40:41], v[34:35], v[34:35]
	v_pk_mul_f32 v[44:45], v[36:37], v[36:37]
	v_pk_mul_f32 v[30:31], v[30:31], v[142:143] op_sel_hi:[1,0]
	v_pk_mul_f32 v[26:27], v[26:27], v[142:143] op_sel_hi:[1,0]
	v_lshl_add_u64 v[50:51], v[140:141], 0, s[26:27]
	v_cvt_pk_f16_f32 v34, v38, v39
	v_cvt_pk_f16_f32 v35, v40, v41
	v_cvt_pk_f16_f32 v36, v42, v43
	v_cvt_pk_f16_f32 v37, v44, v45
	v_pk_mul_f32 v[32:33], v[32:33], v[142:143] op_sel_hi:[1,0]
	v_pk_mul_f32 v[28:29], v[28:29], v[142:143] op_sel_hi:[1,0]
	v_max_f32_e32 v30, 0, v30
	v_max_f32_e32 v26, 0, v26
	v_max_f32_e32 v31, 0, v31
	v_max_f32_e32 v27, 0, v27
	global_store_dwordx4 v[50:51], v[34:37], off offset:256 sc1 nt
	v_pk_mul_f32 v[30:31], v[30:31], v[30:31]
	v_max_f32_e32 v28, 0, v28
	v_pk_mul_f32 v[36:37], v[26:27], v[26:27]
	v_max_f32_e32 v26, 0, v32
	v_max_f32_e32 v27, 0, v33
	v_max_f32_e32 v29, 0, v29
	s_mov_b32 s21, 0x140000
	v_pk_mul_f32 v[32:33], v[26:27], v[26:27]
	v_pk_mul_f32 v[38:39], v[28:29], v[28:29]
	v_cvt_pk_f16_f32 v26, v30, v31
	v_add_co_u32_e32 v30, vcc, s21, v140
	v_pk_mul_f32 v[18:19], v[18:19], v[142:143] op_sel_hi:[1,0]
	v_cvt_pk_f16_f32 v27, v32, v33
	v_cvt_pk_f16_f32 v28, v36, v37
	v_cvt_pk_f16_f32 v29, v38, v39
	v_addc_co_u32_e32 v31, vcc, 0, v141, vcc
	v_pk_mul_f32 v[24:25], v[24:25], v[142:143] op_sel_hi:[1,0]
	v_pk_mul_f32 v[22:23], v[22:23], v[142:143] op_sel_hi:[1,0]
	v_pk_mul_f32 v[20:21], v[20:21], v[142:143] op_sel_hi:[1,0]
	v_max_f32_e32 v18, 0, v18
	v_max_f32_e32 v19, 0, v19
	global_store_dwordx4 v[30:31], v[26:29], off sc1 nt
	v_max_f32_e32 v22, 0, v22
	v_max_f32_e32 v23, 0, v23
	v_pk_mul_f32 v[26:27], v[18:19], v[18:19]
	v_max_f32_e32 v18, 0, v24
	v_max_f32_e32 v20, 0, v20
	v_max_f32_e32 v19, 0, v25
	v_max_f32_e32 v21, 0, v21
	s_mov_b64 s[26:27], 0x140000
	v_pk_mul_f32 v[22:23], v[22:23], v[22:23]
	v_pk_mul_f32 v[24:25], v[18:19], v[18:19]
	v_pk_mul_f32 v[28:29], v[20:21], v[20:21]
	v_lshl_add_u64 v[34:35], v[140:141], 0, s[26:27]
	v_cvt_pk_f16_f32 v18, v22, v23
	v_cvt_pk_f16_f32 v19, v24, v25
	v_cvt_pk_f16_f32 v20, v26, v27
	v_cvt_pk_f16_f32 v21, v28, v29
	global_store_dwordx4 v[34:35], v[18:21], off offset:256 sc1 nt
	s_mov_b32 s21, 0x160000
	s_mov_b64 s[26:27], 0x160000
	v_mov_b32_e32 v20, v143
	v_pk_mul_f32 v[14:15], v[14:15], v[20:21] op_sel_hi:[1,0]
	v_pk_mul_f32 v[10:11], v[10:11], v[20:21] op_sel_hi:[1,0]
	v_pk_mul_f32 v[16:17], v[16:17], v[20:21] op_sel_hi:[1,0]
	v_pk_mul_f32 v[12:13], v[12:13], v[20:21] op_sel_hi:[1,0]
	v_max_f32_e32 v14, 0, v14
	v_max_f32_e32 v10, 0, v10
	v_max_f32_e32 v15, 0, v15
	v_max_f32_e32 v11, 0, v11
	v_pk_mul_f32 v[14:15], v[14:15], v[14:15]
	v_pk_mul_f32 v[22:23], v[10:11], v[10:11]
	v_max_f32_e32 v10, 0, v16
	v_max_f32_e32 v12, 0, v12
	v_max_f32_e32 v11, 0, v17
	v_max_f32_e32 v13, 0, v13
	v_pk_mul_f32 v[16:17], v[10:11], v[10:11]
	v_pk_mul_f32 v[24:25], v[12:13], v[12:13]
	v_cvt_pk_f16_f32 v10, v14, v15
	v_add_co_u32_e32 v14, vcc, s21, v140
	v_pk_mul_f32 v[2:3], v[2:3], v[20:21] op_sel_hi:[1,0]
	v_cvt_pk_f16_f32 v11, v16, v17
	v_cvt_pk_f16_f32 v12, v22, v23
	v_cvt_pk_f16_f32 v13, v24, v25
	v_addc_co_u32_e32 v15, vcc, 0, v141, vcc
	v_pk_mul_f32 v[8:9], v[8:9], v[20:21] op_sel_hi:[1,0]
	v_pk_mul_f32 v[6:7], v[6:7], v[20:21] op_sel_hi:[1,0]
	v_pk_mul_f32 v[4:5], v[4:5], v[20:21] op_sel_hi:[1,0]
	v_max_f32_e32 v2, 0, v2
	v_max_f32_e32 v3, 0, v3
	global_store_dwordx4 v[14:15], v[10:13], off sc1 nt
	v_max_f32_e32 v6, 0, v6
	v_max_f32_e32 v7, 0, v7
	v_pk_mul_f32 v[10:11], v[2:3], v[2:3]
	v_max_f32_e32 v2, 0, v8
	v_max_f32_e32 v4, 0, v4
	v_max_f32_e32 v3, 0, v9
	v_max_f32_e32 v5, 0, v5
	v_pk_mul_f32 v[6:7], v[6:7], v[6:7]
	v_pk_mul_f32 v[8:9], v[2:3], v[2:3]
	v_pk_mul_f32 v[12:13], v[4:5], v[4:5]
	v_readlane_b32 s76, v253, 5
	v_lshl_add_u64 v[18:19], v[140:141], 0, s[26:27]
	v_cvt_pk_f16_f32 v2, v6, v7
	v_cvt_pk_f16_f32 v3, v8, v9
	v_cvt_pk_f16_f32 v4, v10, v11
	v_cvt_pk_f16_f32 v5, v12, v13
	s_andn2_b64 vcc, exec, s[38:39]
	s_mov_b64 s[26:27], -1
	v_readlane_b32 s77, v253, 6
	v_readlane_b32 s78, v253, 7
	v_readlane_b32 s79, v253, 8
	s_mov_b32 s72, s93
	s_mov_b32 s93, s16
	global_store_dwordx4 v[18:19], v[2:5], off offset:256 sc1 nt
	s_cbranch_vccnz .LBB0_959
	s_andn2_b64 vcc, exec, s[0:1]
	s_cbranch_vccnz .LBB0_958
	s_barrier
	s_branch .LBB0_958
